# scan: S8 hand-scheduled consumer body + parts A/B moved to consumer waves with stores/gate loads spread inside the MFMA body (AB3), V via LDS-DMA
# baseline (speedup 1.0000x reference)
.LBB0_288:
	s_add_i32 s0, s17, 31
	s_lshr_b32 s18, s0, 5
	s_add_i32 s0, s18, 3
	s_and_b32 s19, s0, 0x46
	s_cmp_eq_u32 s19, 0
	s_cbranch_scc1 .LBB0_283
	s_and_b32 s0, s16, 15
	s_add_i32 s20, s18, -1
	s_ashr_i32 s9, s8, 31
	s_cmp_eq_u32 s20, 0
	v_add_u32_e32 v56, s8, v176
	s_cselect_b32 s1, 0, 32
	s_waitcnt vmcnt(0)
	v_add_u32_e32 v20, s1, v56
	v_ashrrev_i32_e32 v21, 31, v20
	v_lshl_add_u32 v58, s0, 7, v55
	v_mov_b32_e32 v59, v2
	v_lshlrev_b64 v[20:21], 11, v[20:21]
	v_lshl_add_u64 v[20:21], v[20:21], 0, v[58:59]
	v_lshlrev_b64 v[22:23], 1, v[20:21]
	v_lshl_add_u64 v[24:25], s[72:73], 0, v[22:23]
	v_add_co_u32_e32 v26, vcc, s33, v24
	v_lshl_add_u64 v[22:23], s[64:65], 0, v[22:23]
	s_nop 0
	v_addc_co_u32_e32 v27, vcc, 0, v25, vcc
	v_add_co_u32_e32 v28, vcc, s33, v22
	v_lshl_add_u64 v[20:21], v[20:21], 2, s[74:75]
	s_nop 0
	v_addc_co_u32_e32 v29, vcc, 0, v23, vcc
	s_mov_b32 s3, 0xe000
	v_add_co_u32_e32 v30, vcc, s3, v20
	v_readlane_b32 s10, v251, 37
	s_nop 0
	v_addc_co_u32_e32 v31, vcc, 0, v21, vcc
	v_readlane_b32 s11, v251, 38
	v_add_co_u32_e32 v32, vcc, s63, v24
	v_lshl_add_u32 v6, s0, 8, v53
	v_mov_b64_e32 v[4:5], s[10:11]
	v_addc_co_u32_e32 v33, vcc, 0, v25, vcc
	v_mad_i64_i32 v[4:5], s[10:11], v6, s93, v[4:5]
	v_add_co_u32_e32 v34, vcc, s63, v22
	v_readlane_b32 s10, v253, 63
	s_nop 0
	v_addc_co_u32_e32 v35, vcc, 0, v23, vcc
	v_lshl_add_u64 v[60:61], s[8:9], 1, v[4:5]
	v_readlane_b32 s11, v254, 0
	s_lshl_b32 s10, s1, 1
	v_add_co_u32_e32 v62, vcc, s67, v20
	v_lshl_add_u64 v[16:17], v[60:61], 0, s[10:11]
	s_nop 0
	v_addc_co_u32_e32 v63, vcc, 0, v21, vcc
	s_movk_i32 s10, 0x5000
	s_nop 0
	s_nop 0
	global_load_dwordx2 v[64:65], v[30:31], off
	global_load_dword v196, v[32:33], off
	global_load_dword v189, v[34:35], off
	global_load_dwordx2 v[66:67], v[62:63], off
	v_add_co_u32_e32 v30, vcc, s10, v24
	s_mov_b32 s9, 0xa000
	s_nop 0
	v_addc_co_u32_e32 v31, vcc, 0, v25, vcc
	v_add_co_u32_e32 v32, vcc, s10, v22
	s_mov_b32 s1, 0x8000
	s_nop 0
	v_addc_co_u32_e32 v33, vcc, 0, v23, vcc
	v_add_co_u32_e32 v34, vcc, s9, v20
	s_movk_i32 s12, 0x3000
	s_nop 0
	v_addc_co_u32_e32 v35, vcc, 0, v21, vcc
	v_add_co_u32_e32 v68, vcc, s66, v24
	s_movk_i32 s13, 0x1000
	s_nop 0
	v_addc_co_u32_e32 v69, vcc, 0, v25, vcc
	v_add_co_u32_e32 v70, vcc, s66, v22
	v_ashrrev_i32_e32 v57, 31, v56
	s_nop 0
	v_addc_co_u32_e32 v71, vcc, 0, v23, vcc
	global_load_dword v198, v[30:31], off
	global_load_dword v192, v[32:33], off
	global_load_dwordx2 v[62:63], v[34:35], off
	global_load_dword v197, v[68:69], off
	global_load_dword v190, v[70:71], off
	v_add_co_u32_e32 v30, vcc, s1, v20
	v_lshlrev_b64 v[78:79], 11, v[56:57]
	s_nop 0
	v_addc_co_u32_e32 v31, vcc, 0, v21, vcc
	v_add_co_u32_e32 v32, vcc, s12, v24
	v_lshl_add_u64 v[78:79], v[78:79], 0, v[58:59]
	s_nop 0
	v_addc_co_u32_e32 v33, vcc, 0, v25, vcc
	v_add_co_u32_e32 v34, vcc, s12, v22
	v_lshlrev_b64 v[80:81], 1, v[78:79]
	s_nop 0
	v_addc_co_u32_e32 v35, vcc, 0, v23, vcc
	v_add_co_u32_e32 v68, vcc, s63, v20
	v_lshl_add_u64 v[82:83], s[72:73], 0, v[80:81]
	s_nop 0
	v_addc_co_u32_e32 v69, vcc, 0, v21, vcc
	global_load_dwordx2 v[70:71], v[30:31], off
	global_load_dword v200, v[32:33], off
	global_load_dword v191, v[34:35], off
	global_load_dwordx2 v[72:73], v[68:69], off
	v_add_co_u32_e32 v30, vcc, s69, v24
	v_lshl_add_u64 v[80:81], s[64:65], 0, v[80:81]
	s_nop 0
	v_addc_co_u32_e32 v31, vcc, 0, v25, vcc
	v_add_co_u32_e32 v32, vcc, s69, v22
	v_lshl_add_u64 v[78:79], v[78:79], 2, s[74:75]
	s_nop 0
	v_addc_co_u32_e32 v33, vcc, 0, v23, vcc
	v_add_co_u32_e32 v34, vcc, s66, v20
	v_xor_b32_e32 v57, 1, v208
	s_nop 0
	v_addc_co_u32_e32 v35, vcc, 0, v21, vcc
	v_add_co_u32_e32 v68, vcc, s13, v24
	s_mov_b32 s28, 0xe000
	s_nop 0
	v_addc_co_u32_e32 v69, vcc, 0, v25, vcc
	v_add_co_u32_e32 v74, vcc, s13, v22
	s_mov_b32 s47, 0x8000
	s_nop 0
	v_addc_co_u32_e32 v75, vcc, 0, v23, vcc
	global_load_dword v202, v[30:31], off
	global_load_dword v195, v[32:33], off
	global_load_dwordx2 v[76:77], v[34:35], off
	global_load_dword v215, v[68:69], off
	global_load_dword v194, v[74:75], off
	v_add_co_u32_e32 v74, vcc, s69, v20
	s_mov_b32 s24, 0
	s_nop 0
	v_addc_co_u32_e32 v75, vcc, 0, v21, vcc
	v_add_co_u32_e32 v84, vcc, s33, v82
	global_load_dword v225, v[26:27], off
	global_load_dword v199, v[28:29], off
	global_load_dwordx2 v[68:69], v[20:21], off
	global_load_dword v193, v[22:23], off
	global_load_dword v201, v[24:25], off
	s_nop 0
	v_addc_co_u32_e32 v85, vcc, 0, v83, vcc
	v_add_co_u32_e32 v86, vcc, s33, v80
	v_add_u32_e32 v217, s8, v175
	s_nop 0
	v_addc_co_u32_e32 v87, vcc, 0, v81, vcc
	v_add_co_u32_e32 v88, vcc, s3, v78
	s_mov_b32 s3, 0xa000
	s_nop 0
	v_addc_co_u32_e32 v89, vcc, 0, v79, vcc
	v_add_co_u32_e32 v92, vcc, s63, v82
	s_add_i32 s21, s8, 32
	s_nop 0
	v_addc_co_u32_e32 v93, vcc, 0, v83, vcc
	v_add_co_u32_e32 v94, vcc, s63, v80
	s_sub_i32 s22, s17, 32
	s_nop 0
	v_addc_co_u32_e32 v95, vcc, 0, v81, vcc
	v_add_co_u32_e32 v90, vcc, s67, v78
	v_mov_b32_e32 v112, 0
	s_nop 0
	v_addc_co_u32_e32 v91, vcc, 0, v79, vcc
	v_add_co_u32_e32 v96, vcc, s10, v82
	v_mov_b32_e32 v113, 0
	s_nop 0
	v_addc_co_u32_e32 v97, vcc, 0, v83, vcc
	v_add_co_u32_e32 v98, vcc, s10, v80
	s_lshl_b32 s10, s0, 9
	s_nop 0
	v_addc_co_u32_e32 v99, vcc, 0, v81, vcc
	v_add_co_u32_e32 v100, vcc, s9, v78
	s_mov_b32 s9, 1
	s_nop 0
	v_addc_co_u32_e32 v101, vcc, 0, v79, vcc
	global_load_dwordx2 v[108:109], v[90:91], off
	global_load_dword v229, v[96:97], off
	global_load_dword v221, v[98:99], off
	s_nop 0
	global_load_dwordx2 v[90:91], v[100:101], off
	v_add_co_u32_e32 v96, vcc, s66, v82
	v_mov_b32_e32 v120, 0
	s_nop 0
	v_addc_co_u32_e32 v97, vcc, 0, v83, vcc
	v_add_co_u32_e32 v98, vcc, s66, v80
	v_mov_b32_e32 v121, 0
	s_nop 0
	v_addc_co_u32_e32 v99, vcc, 0, v81, vcc
	v_add_co_u32_e32 v100, vcc, s1, v78
	s_mov_b32 s1, s11
	s_nop 0
	v_addc_co_u32_e32 v101, vcc, 0, v79, vcc
	v_add_co_u32_e32 v102, vcc, s12, v82
	v_writelane_b32 v253, s0, 63
	s_nop 0
	v_addc_co_u32_e32 v103, vcc, 0, v83, vcc
	v_add_co_u32_e32 v104, vcc, s12, v80
	v_writelane_b32 v254, s1, 0
	s_nop 0
	v_addc_co_u32_e32 v105, vcc, 0, v81, vcc
	global_load_dword v231, v[96:97], off
	global_load_dword v223, v[98:99], off
	s_nop 0
	global_load_dwordx2 v[100:101], v[100:101], off
	s_nop 0
	global_load_dword v232, v[102:103], off
	global_load_dword v222, v[104:105], off
	v_add_co_u32_e32 v96, vcc, s63, v78
	v_mov_b32_e32 v124, 0
	s_nop 0
	v_addc_co_u32_e32 v97, vcc, 0, v79, vcc
	v_add_co_u32_e32 v98, vcc, s69, v82
	v_mov_b32_e32 v125, 0
	s_nop 0
	v_addc_co_u32_e32 v99, vcc, 0, v83, vcc
	v_add_co_u32_e32 v102, vcc, s69, v80
	v_mov_b32_e32 v110, 0
	s_nop 0
	v_addc_co_u32_e32 v103, vcc, 0, v81, vcc
	v_add_co_u32_e32 v104, vcc, s66, v78
	v_mov_b32_e32 v111, 0
	s_nop 0
	v_addc_co_u32_e32 v105, vcc, 0, v79, vcc
	global_load_dwordx2 v[114:115], v[96:97], off
	global_load_dword v234, v[98:99], off
	global_load_dword v226, v[102:103], off
	global_load_dwordx2 v[118:119], v[104:105], off
	v_add_co_u32_e32 v96, vcc, s13, v82
	v_mov_b32_e32 v116, 0
	s_nop 0
	v_addc_co_u32_e32 v97, vcc, 0, v83, vcc
	v_add_co_u32_e32 v98, vcc, s13, v80
	v_mov_b32_e32 v117, 0
	s_nop 0
	v_addc_co_u32_e32 v99, vcc, 0, v81, vcc
	v_add_co_u32_e32 v102, vcc, s69, v78
	v_mov_b32_e32 v122, 0
	s_nop 0
	v_addc_co_u32_e32 v103, vcc, 0, v79, vcc
	global_load_dword v235, v[96:97], off
	global_load_dword v227, v[98:99], off
	s_nop 0
	global_load_dwordx2 v[102:103], v[102:103], off
	s_nop 0
	global_load_dwordx2 v[104:105], v[74:75], off
	global_load_dword v237, v[84:85], off
	global_load_dword v230, v[86:87], off
	global_load_dword v224, v[80:81], off
	global_load_dword v233, v[82:83], off
	global_load_dwordx2 v[128:129], v[88:89], off
	global_load_dword v236, v[92:93], off
	global_load_dword v228, v[94:95], off
	global_load_dwordx2 v[106:107], v[78:79], off
	v_and_b32_e32 v80, 64, v208
	v_add_u32_e32 v74, 64, v80
	v_cmp_lt_i32_e32 vcc, v57, v74
	v_xor_b32_e32 v75, 2, v208
	v_add_u32_e32 v81, -16, v208
	v_cndmask_b32_e32 v57, v208, v57, vcc
	v_cmp_lt_i32_e32 vcc, v75, v74
	v_lshlrev_b32_e32 v57, 2, v57
	v_lshl_add_u64 v[78:79], v[38:39], 0, s[10:11]
	v_cndmask_b32_e32 v75, v208, v75, vcc
	v_lshlrev_b32_e32 v203, 2, v75
	v_xor_b32_e32 v75, 4, v208
	v_cmp_lt_i32_e32 vcc, v75, v74
	v_mov_b32_e32 v84, 0
	v_mov_b32_e32 v85, 0
	v_cndmask_b32_e32 v74, v208, v75, vcc
	v_cmp_lt_i32_e32 vcc, v81, v80
	v_lshlrev_b32_e32 v216, 2, v74
	v_lshl_add_u64 v[74:75], v[36:37], 0, s[10:11]
	v_cndmask_b32_e32 v81, v81, v208, vcc
	v_lshlrev_b32_e32 v218, 2, v81
	v_subrev_u32_e32 v81, 32, v208
	v_cmp_lt_i32_e32 vcc, v81, v80
	v_or_b32_e32 v80, v80, v0
	v_lshl_or_b32 v220, v80, 2, v209
	v_cndmask_b32_e32 v81, v81, v208, vcc
	v_lshlrev_b32_e32 v219, 2, v81
	v_mov_b32_e32 v80, 0
	v_mov_b32_e32 v81, 0
	v_mov_b32_e32 v88, 0
	v_mov_b32_e32 v89, 0
	v_mov_b32_e32 v94, 0
	v_mov_b32_e32 v95, 0
	v_mov_b32_e32 v98, 0
	v_mov_b32_e32 v99, 0
	v_mov_b32_e32 v82, 0
	v_mov_b32_e32 v83, 0
	v_mov_b32_e32 v86, 0
	v_mov_b32_e32 v87, 0
	v_mov_b32_e32 v92, 0
	v_mov_b32_e32 v93, 0
	v_mov_b32_e32 v96, 0
	v_mov_b32_e32 v97, 0
	v_mov_b32_e32 v123, 0
	v_mov_b32_e32 v126, 0
	v_mov_b32_e32 v127, 0
	s_mov_b32 s23, s17
	s_waitcnt vmcnt(0)
	s_branch .LBB0_291

.LBB0_295:
	s_min_i32 s1, s24, s20
	s_lshl_b32 s1, s1, 5
	s_sub_i32 s25, s17, s1
	s_cmp_gt_i32 s25, 31
	s_waitcnt vmcnt(24)
	v_lshlrev_b32_e32 v168, 16, v232
	s_mov_b64 s[0:1], -1
	v_lshlrev_b32_e32 v170, 16, v234
	v_lshlrev_b32_e32 v166, 16, v231
	v_lshlrev_b32_e32 v158, 16, v229
	s_cbranch_scc1 .LBB0_297
	s_min_i32 s0, s25, 32
	v_add_f32_e32 v130, 0, v106
	v_cmp_gt_i32_e32 vcc, s0, v176
	v_and_b32_e32 v132, 0xffff0000, v235
	v_and_b32_e32 v134, 0xffff0000, v234
	v_cndmask_b32_e32 v136, 0, v130, vcc
	v_add_f32_e32 v130, 0, v107
	v_cndmask_b32_e32 v139, 0, v130, vcc
	v_lshlrev_b32_e32 v130, 16, v233
	v_cndmask_b32_e32 v131, 0, v130, vcc
	v_and_b32_e32 v130, 0xffff0000, v233
	v_cndmask_b32_e32 v241, 0, v130, vcc
	v_cmp_gt_i32_e32 vcc, s0, v1
	v_lshlrev_b32_e32 v130, 16, v235
	v_and_b32_e32 v135, 0xffff0000, v232
	v_cndmask_b32_e32 v133, 0, v102, vcc
	v_add_f32_e32 v138, v136, v133
	v_cndmask_b32_e32 v239, 0, v130, vcc
	v_cndmask_b32_e32 v240, 0, v132, vcc
	v_cndmask_b32_e32 v133, 0, v103, vcc
	v_cmp_gt_i32_e32 vcc, s0, v40
	v_and_b32_e32 v137, 0xffff0000, v231
	v_and_b32_e32 v140, 0xffff0000, v229
	v_cndmask_b32_e32 v132, 0, v118, vcc
	v_cmp_gt_i32_e32 vcc, s0, v41
	v_pk_add_f32 v[146:147], v[132:133], v[138:139]
	v_lshlrev_b32_e32 v159, 16, v236
	v_cndmask_b32_e32 v157, 0, v134, vcc
	v_cndmask_b32_e32 v156, 0, v170, vcc
	v_cndmask_b32_e32 v133, 0, v119, vcc
	v_cmp_gt_i32_e32 vcc, s0, v54
	v_lshlrev_b32_e32 v162, 16, v237
	v_and_b32_e32 v163, 0xffff0000, v236
	v_cndmask_b32_e32 v132, 0, v114, vcc
	v_cmp_gt_i32_e32 vcc, s0, v3
	v_pk_add_f32 v[148:149], v[132:133], v[146:147]
	s_nop 0
	v_cndmask_b32_e32 v155, 0, v135, vcc
	v_cndmask_b32_e32 v154, 0, v168, vcc
	v_cndmask_b32_e32 v133, 0, v115, vcc
	v_cmp_gt_i32_e32 vcc, s0, v52
	s_nop 1
	v_cndmask_b32_e32 v132, 0, v100, vcc
	v_cmp_gt_i32_e32 vcc, s0, v43
	v_pk_add_f32 v[142:143], v[132:133], v[148:149]
	s_nop 0
	v_cndmask_b32_e32 v153, 0, v137, vcc
	v_cndmask_b32_e32 v152, 0, v166, vcc
	v_cndmask_b32_e32 v133, 0, v101, vcc
	v_cmp_gt_i32_e32 vcc, s0, v42
	s_nop 1
	v_cndmask_b32_e32 v132, 0, v90, vcc
	v_cmp_gt_i32_e32 vcc, s0, v51
	v_pk_add_f32 v[144:145], v[132:133], v[142:143]
	s_nop 0
	v_cndmask_b32_e32 v151, 0, v140, vcc
	v_cndmask_b32_e32 v150, 0, v158, vcc
	v_cndmask_b32_e32 v133, 0, v91, vcc
	v_cmp_gt_i32_e32 vcc, s0, v50
	s_nop 1
	v_cndmask_b32_e32 v132, 0, v108, vcc
	v_cmp_gt_i32_e32 vcc, s0, v45
	v_cmp_gt_i32_e64 s[0:1], s0, v44
	v_pk_add_f32 v[140:141], v[132:133], v[144:145]
	v_cndmask_b32_e32 v133, 0, v109, vcc
	v_cndmask_b32_e64 v132, 0, v128, s[0:1]
	v_cndmask_b32_e32 v130, 0, v159, vcc
	v_pk_add_f32 v[134:135], v[132:133], v[140:141]
	v_cndmask_b32_e64 v132, 0, v129, s[0:1]
	v_and_b32_e32 v159, 0xffff0000, v237
	v_add_f32_e32 v137, v132, v135
	v_cndmask_b32_e32 v133, 0, v163, vcc
	v_cndmask_b32_e64 v132, 0, v162, s[0:1]
	v_cndmask_b32_e64 v238, 0, v159, s[0:1]
	s_mov_b64 s[0:1], 0

.LBB0_305:
	s_add_i32 s10, s24, 1
	s_min_i32 s10, s10, s20
	s_lshl_b32 s10, s10, 5
	s_mov_b64 s[0:1], -1
	s_waitcnt vmcnt(24)
	s_sub_i32 s10, s17, s10
	s_cmp_gt_i32 s10, 31
	s_cbranch_scc1 .LBB0_307
	s_min_i32 s10, s10, 32
	v_add_f32_e32 v130, 0, v68
	v_cmp_gt_i32_e32 vcc, s10, v176
	v_cmp_gt_i32_e64 s[0:1], s10, v40
	v_and_b32_e32 v133, 0xffff0000, v215
	v_cndmask_b32_e32 v144, 0, v130, vcc
	v_add_f32_e32 v130, 0, v69
	v_cndmask_b32_e32 v143, 0, v130, vcc
	v_lshlrev_b32_e32 v130, 16, v201
	v_cndmask_b32_e32 v141, 0, v130, vcc
	v_and_b32_e32 v130, 0xffff0000, v201
	v_cndmask_b32_e32 v169, 0, v130, vcc
	v_cmp_gt_i32_e32 vcc, s10, v1
	v_lshlrev_b32_e32 v132, 16, v202
	v_cndmask_b32_e64 v138, 0, v132, s[0:1]
	v_cndmask_b32_e32 v130, 0, v104, vcc
	v_add_f32_e32 v142, v144, v130
	v_lshlrev_b32_e32 v130, 16, v215
	v_cndmask_b32_e32 v140, 0, v130, vcc
	v_cndmask_b32_e32 v131, 0, v105, vcc
	v_cndmask_b32_e64 v130, 0, v76, s[0:1]
	v_pk_add_f32 v[146:147], v[130:131], v[142:143]
	v_cndmask_b32_e64 v130, 0, v77, s[0:1]
	v_add_f32_e32 v241, v130, v147
	v_cndmask_b32_e32 v139, 0, v133, vcc
	v_and_b32_e32 v130, 0xffff0000, v202
	v_cmp_gt_i32_e32 vcc, s10, v3
	v_cndmask_b32_e64 v166, 0, v130, s[0:1]
	v_and_b32_e32 v131, 0xffff0000, v197
	v_cndmask_b32_e32 v130, 0, v72, vcc
	v_add_f32_e32 v239, v130, v146
	v_cndmask_b32_e32 v130, 0, v73, vcc
	v_add_f32_e32 v240, v130, v241
	v_lshlrev_b32_e32 v130, 16, v200
	v_cndmask_b32_e32 v135, 0, v130, vcc
	v_and_b32_e32 v130, 0xffff0000, v200
	v_cndmask_b32_e32 v159, 0, v130, vcc
	v_cmp_gt_i32_e32 vcc, s10, v43
	v_cmp_gt_i32_e64 s[0:1], s10, v42
	v_and_b32_e32 v133, 0xffff0000, v196
	v_cndmask_b32_e32 v130, 0, v70, vcc
	v_add_f32_e32 v173, v130, v239
	v_cndmask_b32_e32 v130, 0, v71, vcc
	v_add_f32_e32 v238, v130, v240
	v_lshlrev_b32_e32 v130, 16, v197
	v_cndmask_b32_e32 v134, 0, v130, vcc
	v_lshlrev_b32_e32 v130, 16, v198
	v_cndmask_b32_e64 v132, 0, v62, s[0:1]
	v_cndmask_b32_e32 v137, 0, v131, vcc
	v_cndmask_b32_e64 v136, 0, v130, s[0:1]
	v_and_b32_e32 v130, 0xffff0000, v198
	v_cmp_gt_i32_e32 vcc, s10, v45
	v_add_f32_e32 v171, v132, v173
	v_cndmask_b32_e64 v132, 0, v63, s[0:1]
	v_cndmask_b32_e64 v131, 0, v130, s[0:1]
	v_cndmask_b32_e32 v130, 0, v66, vcc
	v_add_f32_e32 v172, v132, v238
	v_add_f32_e32 v168, v130, v171
	v_cndmask_b32_e32 v130, 0, v67, vcc
	v_cmp_gt_i32_e64 s[0:1], s10, v44
	v_add_f32_e32 v170, v130, v172
	v_lshlrev_b32_e32 v130, 16, v196
	v_cndmask_b32_e64 v148, 0, v65, s[0:1]
	v_lshlrev_b32_e32 v132, 16, v225
	v_cndmask_b32_e64 v145, 0, v64, s[0:1]
	v_add_f32_e32 v167, v148, v170
	v_and_b32_e32 v148, 0xffff0000, v225
	v_cndmask_b32_e32 v130, 0, v130, vcc
	v_add_f32_e32 v145, v145, v168
	v_cndmask_b32_e32 v133, 0, v133, vcc
	v_cndmask_b32_e64 v132, 0, v132, s[0:1]
	v_cndmask_b32_e64 v158, 0, v148, s[0:1]
	s_mov_b64 s[0:1], 0

.LBB0_312:
	s_andn2_b64 vcc, exec, s[0:1]
	s_cbranch_vccnz .LBB0_324
	s_and_b64 vcc, exec, s[38:39]
	s_cbranch_vccnz .LBB0_324
	s_and_b32 s0, s15, 0xffffffc0
	s_lshl_b32 s1, s0, 2
	s_waitcnt lgkmcnt(0)
	v_lshrrev_b32_e32 v3, 2, v161
	s_add_i32 s8, s1, 0
	s_waitcnt vmcnt(0)
	v_bfe_u32 v5, v161, 2, 2
	v_bitop3_b32 v3, v47, v3, 3 bitop3:0x78
	v_lshlrev_b32_e32 v4, 2, v0
	v_readlane_b32 s10, v255, 1
	v_lshlrev_b32_e32 v1, 2, v47
	v_lshlrev_b32_e32 v173, 3, v3
	v_bitop3_b32 v3, v47, v5, 4 bitop3:0x36
	s_add_i32 s8, s8, 0x15800
	v_readlane_b32 s11, v255, 2
	s_mov_b32 s12, s10
	s_ashr_i32 s1, s0, 31
	v_lshlrev_b32_e32 v172, 3, v47
	v_lshlrev_b32_e32 v175, 3, v3
	v_lshrrev_b32_e32 v229, 1, v47
	v_bfe_u32 v230, v161, 2, 2
	v_xor_b32_e32 v229, v229, v230
	v_and_b32_e32 v230, 1, v47
	v_lshlrev_b32_e32 v230, 3, v230
	v_lshl_add_u32 v173, v229, 4, v230
	v_xor_b32_e32 v175, 32, v173
	v_lshrrev_b32_e32 v229, 2, v174
	v_mul_u32_u24_e32 v228, 0x4400, v229
	v_bfe_u32 v229, v174, 4, 2
	v_and_b32_e32 v230, 3, v174
	v_xor_b32_e32 v229, v229, v230
	v_lshl_add_u32 v228, v229, 4, v228
	v_lshrrev_b32_e32 v229, 3, v161
	v_and_b32_e32 v230, 7, v161
	v_lshlrev_b32_e32 v231, 13, v229
	v_lshl_add_u32 v231, v230, 4, v231
	v_mul_u32_u24_e32 v248, 0x410, v229
	v_lshl_add_u32 v248, v230, 5, v248
	v_add_u32_e32 v248, 0x15800, v248
	v_add_u32_e32 v177, s8, v4
	s_movk_i32 s8, 0x108
	v_cmp_gt_u32_e64 s[38:39], v1, v0
	v_cmp_lt_u32_e64 s[40:41], v1, v0
	v_or_b32_e32 v3, 2, v1
	v_or_b32_e32 v1, 3, v1
	v_readlane_b32 s16, v251, 55
	s_lshl_b32 s10, s10, 9
	s_and_b32 s9, s15, 0x3ffffc0
	s_lshl_b32 s11, s12, 6
	v_mad_u32_u24 v179, v0, s8, v172
	v_cmp_gt_u32_e64 s[44:45], v1, v0
	s_movk_i32 s8, 0x50
	v_mov_b32_e32 v1, 0x500
	s_lshl_b64 s[0:1], s[0:1], 2
	v_readlane_b32 s20, v251, 59
	v_mad_u32_u24 v183, v0, s8, v1
	v_readlane_b32 s21, v251, 60
	s_add_u32 s8, s20, s0
	v_or_b32_e32 v7, s9, v0
	s_addc_u32 s9, s21, s1
	v_mov_b32_e32 v5, v2
	v_lshlrev_b32_e32 v6, 10, v47
	v_readlane_b32 s24, v251, 63
	v_readlane_b32 s25, v252, 0
	v_readlane_b32 s26, v252, 1
	v_readlane_b32 s27, v252, 2
	v_lshl_add_u64 v[4:5], s[8:9], 0, v[4:5]
	v_lshlrev_b32_e32 v8, 12, v47
	v_mov_b32_e32 v9, v2
	v_and_b32_e32 v176, 48, v161
	v_mul_u32_u24_e32 v178, 0x108, v0
	v_add_u32_e32 v180, 0x1080, v179
	v_cmp_gt_u32_e64 s[42:43], v3, v0
	v_lshlrev_b32_e32 v181, 6, v7
	v_mul_u32_u24_e32 v182, 0x50, v0
	v_mul_u32_u24_e32 v184, 0x1040, v47
	v_mul_u32_u24_e32 v185, 0x410, v3
	v_lshl_add_u64 v[166:167], v[4:5], 0, v[8:9]
	v_lshlrev_b32_e32 v168, 2, v0
	v_lshlrev_b32_e32 v170, 2, v6
	s_mov_b32 s12, s2
	s_mov_b32 s24, 0x10000
	s_mov_b32 s25, 0x14000
	s_mov_b32 s26, 0x18000
	s_mov_b32 s27, 0x1c000
	v_readlane_b32 s17, v251, 56
	v_readlane_b32 s18, v251, 57
	v_readlane_b32 s19, v251, 58
	v_readlane_b32 s22, v251, 61
	v_readlane_b32 s23, v251, 62
	v_readlane_b32 s28, v252, 3
	v_readlane_b32 s29, v252, 4
	v_readlane_b32 s30, v252, 5
	v_readlane_b32 s31, v252, 6
	s_branch .LBB0_316

.LBB0_316:
	v_readlane_b32 s100, v251, 37
	v_readlane_b32 s101, v251, 38
	s_lshr_b32 s98, s12, 4
	s_mul_i32 s99, s98, 0x810
	s_sub_i32 s98, s98, 4
	s_lshl_b32 s98, s98, 3
	s_addk_i32 s98, 0x2040
	s_cmp_lt_i32 s12, 64
	s_cselect_b32 s98, s99, s98
	s_lshl_b32 s98, s98, 1
	s_and_b32 s99, s12, 15
	s_mul_i32 s99, s99, 0x440000
	s_add_i32 s98, s98, s99
	s_mul_i32 s99, s14, 0x110000
	s_add_i32 s98, s98, s99
	s_add_u32 s98, s100, s98
	s_addc_u32 s99, s101, 0
	s_lshr_b32 s96, s12, 4
	s_mul_i32 s97, s96, 0x810
	s_sub_i32 s96, s96, 4
	s_lshl_b32 s96, s96, 3
	s_addk_i32 s96, 0x2040
	s_cmp_lt_i32 s12, 64
	s_cselect_b32 s96, s97, s96
	s_and_b32 s97, s12, 15
	s_lshl_b32 s97, s97, 9
	s_cmp_lt_i32 s12, 64
	s_cselect_b64 s[8:9], -1, 0
	s_and_b32 s15, s12, -16
	s_sub_i32 s16, s15, 64
	s_and_b32 s13, s12, 15
	s_and_b64 vcc, exec, s[8:9]
	s_cbranch_vccnz .LBB0_318
	s_add_i32 s17, s16, s10
	s_or_b32 s18, s17, s13
	s_ashr_i32 s19, s18, 31
	s_lshl_b64 s[18:19], s[18:19], 17
	v_lshl_add_u64 v[0:1], v[166:167], 0, s[18:19]
	v_add_co_u32_e32 v36, vcc, s66, v0
	global_load_dword v4, v[0:1], off
	global_load_dword v5, v[0:1], off offset:1024
	global_load_dword v8, v[0:1], off offset:64
	global_load_dword v9, v[0:1], off offset:1088
	global_load_dword v12, v[0:1], off offset:128
	global_load_dword v13, v[0:1], off offset:1152
	global_load_dword v17, v[0:1], off offset:1216
	global_load_dword v16, v[0:1], off offset:192
	global_load_dword v6, v[0:1], off offset:2048
	global_load_dword v7, v[0:1], off offset:3072
	global_load_dword v10, v[0:1], off offset:2112
	global_load_dword v11, v[0:1], off offset:3136
	global_load_dword v14, v[0:1], off offset:2176
	global_load_dword v15, v[0:1], off offset:3200
	global_load_dword v19, v[0:1], off offset:3264
	global_load_dword v18, v[0:1], off offset:2240
	v_addc_co_u32_e32 v37, vcc, 0, v1, vcc
	v_add_co_u32_e32 v52, vcc, s47, v0
	global_load_dword v20, v[36:37], off
	global_load_dword v21, v[36:37], off offset:1024
	global_load_dword v24, v[36:37], off offset:64
	global_load_dword v25, v[36:37], off offset:1088
	global_load_dword v28, v[36:37], off offset:128
	global_load_dword v29, v[36:37], off offset:1152
	global_load_dword v33, v[36:37], off offset:1216
	global_load_dword v32, v[36:37], off offset:192
	global_load_dword v22, v[36:37], off offset:2048
	global_load_dword v23, v[36:37], off offset:3072
	global_load_dword v26, v[36:37], off offset:2112
	global_load_dword v27, v[36:37], off offset:3136
	global_load_dword v30, v[36:37], off offset:2176
	global_load_dword v31, v[36:37], off offset:3200
	global_load_dword v35, v[36:37], off offset:3264
	global_load_dword v34, v[36:37], off offset:2240
	v_addc_co_u32_e32 v53, vcc, 0, v1, vcc
	v_add_co_u32_e32 v68, vcc, s67, v0
	global_load_dword v36, v[52:53], off
	global_load_dword v37, v[52:53], off offset:1024
	global_load_dword v40, v[52:53], off offset:64
	global_load_dword v41, v[52:53], off offset:1088
	global_load_dword v44, v[52:53], off offset:128
	global_load_dword v45, v[52:53], off offset:1152
	global_load_dword v49, v[52:53], off offset:1216
	global_load_dword v48, v[52:53], off offset:192
	global_load_dword v38, v[52:53], off offset:2048
	global_load_dword v39, v[52:53], off offset:3072
	global_load_dword v42, v[52:53], off offset:2112
	global_load_dword v43, v[52:53], off offset:3136
	global_load_dword v46, v[52:53], off offset:2176
	global_load_dword v47, v[52:53], off offset:3200
	global_load_dword v51, v[52:53], off offset:3264
	global_load_dword v50, v[52:53], off offset:2240
	v_addc_co_u32_e32 v69, vcc, 0, v1, vcc
	v_add_co_u32_e32 v84, vcc, s24, v0
	global_load_dword v52, v[68:69], off
	global_load_dword v53, v[68:69], off offset:1024
	global_load_dword v56, v[68:69], off offset:64
	global_load_dword v57, v[68:69], off offset:1088
	global_load_dword v60, v[68:69], off offset:128
	global_load_dword v61, v[68:69], off offset:1152
	global_load_dword v65, v[68:69], off offset:1216
	global_load_dword v64, v[68:69], off offset:192
	global_load_dword v54, v[68:69], off offset:2048
	global_load_dword v55, v[68:69], off offset:3072
	global_load_dword v58, v[68:69], off offset:2112
	global_load_dword v59, v[68:69], off offset:3136
	global_load_dword v62, v[68:69], off offset:2176
	global_load_dword v63, v[68:69], off offset:3200
	global_load_dword v67, v[68:69], off offset:3264
	global_load_dword v66, v[68:69], off offset:2240
	v_addc_co_u32_e32 v85, vcc, 0, v1, vcc
	v_add_co_u32_e32 v100, vcc, s25, v0
	global_load_dword v68, v[84:85], off
	global_load_dword v69, v[84:85], off offset:1024
	global_load_dword v72, v[84:85], off offset:64
	global_load_dword v73, v[84:85], off offset:1088
	global_load_dword v76, v[84:85], off offset:128
	global_load_dword v77, v[84:85], off offset:1152
	global_load_dword v81, v[84:85], off offset:1216
	global_load_dword v80, v[84:85], off offset:192
	global_load_dword v70, v[84:85], off offset:2048
	global_load_dword v71, v[84:85], off offset:3072
	global_load_dword v74, v[84:85], off offset:2112
	global_load_dword v75, v[84:85], off offset:3136
	global_load_dword v78, v[84:85], off offset:2176
	global_load_dword v79, v[84:85], off offset:3200
	global_load_dword v83, v[84:85], off offset:3264
	global_load_dword v82, v[84:85], off offset:2240
	v_addc_co_u32_e32 v101, vcc, 0, v1, vcc
	v_add_co_u32_e32 v116, vcc, s26, v0
	global_load_dword v84, v[100:101], off
	global_load_dword v85, v[100:101], off offset:1024
	global_load_dword v88, v[100:101], off offset:64
	global_load_dword v89, v[100:101], off offset:1088
	global_load_dword v92, v[100:101], off offset:128
	global_load_dword v93, v[100:101], off offset:1152
	global_load_dword v97, v[100:101], off offset:1216
	global_load_dword v96, v[100:101], off offset:192
	global_load_dword v86, v[100:101], off offset:2048
	global_load_dword v87, v[100:101], off offset:3072
	global_load_dword v90, v[100:101], off offset:2112
	global_load_dword v91, v[100:101], off offset:3136
	global_load_dword v94, v[100:101], off offset:2176
	global_load_dword v95, v[100:101], off offset:3200
	global_load_dword v99, v[100:101], off offset:3264
	global_load_dword v98, v[100:101], off offset:2240
	v_addc_co_u32_e32 v117, vcc, 0, v1, vcc
	v_add_co_u32_e32 v0, vcc, s27, v0
	global_load_dword v100, v[116:117], off
	global_load_dword v101, v[116:117], off offset:1024
	global_load_dword v104, v[116:117], off offset:64
	global_load_dword v105, v[116:117], off offset:1088
	global_load_dword v108, v[116:117], off offset:128
	global_load_dword v109, v[116:117], off offset:1152
	global_load_dword v113, v[116:117], off offset:1216
	global_load_dword v112, v[116:117], off offset:192
	global_load_dword v102, v[116:117], off offset:2048
	global_load_dword v103, v[116:117], off offset:3072
	global_load_dword v106, v[116:117], off offset:2112
	global_load_dword v107, v[116:117], off offset:3136
	global_load_dword v110, v[116:117], off offset:2176
	global_load_dword v111, v[116:117], off offset:3200
	global_load_dword v115, v[116:117], off offset:3264
	global_load_dword v114, v[116:117], off offset:2240
	v_addc_co_u32_e32 v1, vcc, 0, v1, vcc
	global_load_dword v124, v[0:1], off
	global_load_dword v125, v[0:1], off offset:1024
	global_load_dword v116, v[0:1], off offset:64
	global_load_dword v117, v[0:1], off offset:1088
	global_load_dword v120, v[0:1], off offset:128
	global_load_dword v121, v[0:1], off offset:1152
	global_load_dword v129, v[0:1], off offset:1216
	global_load_dword v128, v[0:1], off offset:192
	global_load_dword v126, v[0:1], off offset:2048
	global_load_dword v127, v[0:1], off offset:3072
	global_load_dword v118, v[0:1], off offset:2112
	global_load_dword v119, v[0:1], off offset:3136
	global_load_dword v122, v[0:1], off offset:2176
	global_load_dword v123, v[0:1], off offset:3200
	global_load_dword v131, v[0:1], off offset:3264
	global_load_dword v130, v[0:1], off offset:2240
	s_branch .LBB0_319

.LBB0_320:
	s_add_i32 s20, s19, -1
	s_cmp_ge_u32 s20, s17
	s_cbranch_scc1 .Lscan_bar_full
	s_waitcnt vmcnt(8) lgkmcnt(0)
	s_branch .Lscan_bar_go

.Lscan_bar_go:
	s_barrier
	s_add_i32 s19, s19, 1
	s_cmp_eq_u32 s18, s19
	s_cbranch_scc1 .LBB0_315

.Lscan_vdma_skip:
	s_add_i32 s20, s19, -2
	s_cmp_ge_u32 s20, s17
	s_cbranch_scc1 .Lscan_ab_noA
	s_and_b32 s21, s19, 1
	s_mul_i32 s21, s21, 0x8200
	v_add_u32_e32 v200, s21, v248
	ds_read_b128 v[132:135], v200
	ds_read_b128 v[136:139], v200 offset:16
	ds_read_b128 v[140:143], v200 offset:256
	ds_read_b128 v[144:147], v200 offset:272
	ds_read_b128 v[148:151], v200 offset:512
	ds_read_b128 v[152:155], v200 offset:528
	ds_read_b128 v[156:159], v200 offset:768
	ds_read_b128 v[188:191], v200 offset:784
	s_cmp_gt_u32 s17, 1
	s_cselect_b32 s21, 0x810, 8
	s_lshl_b32 s22, s20, 5
	s_sub_i32 s21, s21, s22
	s_min_i32 s21, s21, 32
	s_add_i32 s22, s22, s96
	s_lshl_b32 s22, s22, 13
	s_add_i32 s22, s22, s97
	s_add_i32 s20, s97, 0x4280000
	s_waitcnt lgkmcnt(6)
	v_mul_f32_e32 v192, v132, v132
	v_mul_f32_e32 v193, v133, v133
	v_mul_f32_e32 v194, v134, v134
	v_mul_f32_e32 v195, v135, v135
	v_fmac_f32_e32 v192, v136, v136
	v_fmac_f32_e32 v193, v137, v137
	v_fmac_f32_e32 v194, v138, v138
	v_fmac_f32_e32 v195, v139, v139
	s_waitcnt lgkmcnt(4)
	v_fmac_f32_e32 v192, v140, v140
	v_fmac_f32_e32 v193, v141, v141
	v_fmac_f32_e32 v194, v142, v142
	v_fmac_f32_e32 v195, v143, v143
	v_fmac_f32_e32 v192, v144, v144
	v_fmac_f32_e32 v193, v145, v145
	v_fmac_f32_e32 v194, v146, v146
	v_fmac_f32_e32 v195, v147, v147
	s_waitcnt lgkmcnt(2)
	v_fmac_f32_e32 v192, v148, v148
	v_fmac_f32_e32 v193, v149, v149
	v_fmac_f32_e32 v194, v150, v150
	v_fmac_f32_e32 v195, v151, v151
	v_fmac_f32_e32 v192, v152, v152
	v_fmac_f32_e32 v193, v153, v153
	v_fmac_f32_e32 v194, v154, v154
	v_fmac_f32_e32 v195, v155, v155
	s_waitcnt lgkmcnt(0)
	v_fmac_f32_e32 v192, v156, v156
	v_fmac_f32_e32 v193, v157, v157
	v_fmac_f32_e32 v194, v158, v158
	v_fmac_f32_e32 v195, v159, v159
	v_fmac_f32_e32 v192, v188, v188
	v_fmac_f32_e32 v193, v189, v189
	v_fmac_f32_e32 v194, v190, v190
	v_fmac_f32_e32 v195, v191, v191
	v_add_f32_e32 v192, v192, v193
	v_add_f32_e32 v194, v194, v195
	v_add_f32_e32 v198, v192, v194
	s_nop 1
	v_add_f32_dpp v198, v198, v198 quad_perm:[1,0,3,2] row_mask:0xf bank_mask:0xf
	s_nop 1
	v_add_f32_dpp v198, v198, v198 quad_perm:[2,3,0,1] row_mask:0xf bank_mask:0xf
	s_nop 1
	v_add_f32_dpp v198, v198, v198 row_half_mirror row_mask:0xf bank_mask:0xf
	v_fmamk_f32 v198, v198, 0x3b800000, v206
	v_rsq_f32_e32 v198, v198
	s_cmp_ge_u32 s19, s17
	s_cbranch_scc1 .Lscan_ab_w0
	s_waitcnt vmcnt(4)
	s_branch .Lscan_ab_w1

.Lscan_ab_w1:
	v_lshrrev_b32_e32 v201, 13, v231
	v_cmp_gt_i32_e32 vcc, s21, v201
	v_mov_b32_e32 v201, s20
	v_mov_b32_e32 v202, s22
	v_cndmask_b32_e32 v201, v201, v202, vcc
	v_add_u32_e32 v249, v201, v231
	v_pk_mul_f32 v[132:133], v[132:133], v[198:199] op_sel_hi:[1,0]
	v_lshlrev_b32_e32 v196, 16, v232
	v_and_b32_e32 v197, 0xffff0000, v232
	v_pk_mul_f32 v[132:133], v[132:133], v[196:197]
	v_cvt_pk_bf16_f32 v232, v132, v133
	v_pk_mul_f32 v[134:135], v[134:135], v[198:199] op_sel_hi:[1,0]
	v_lshlrev_b32_e32 v196, 16, v233
	v_and_b32_e32 v197, 0xffff0000, v233
	v_pk_mul_f32 v[134:135], v[134:135], v[196:197]
	v_cvt_pk_bf16_f32 v233, v134, v135
	v_pk_mul_f32 v[136:137], v[136:137], v[198:199] op_sel_hi:[1,0]
	v_lshlrev_b32_e32 v196, 16, v234
	v_and_b32_e32 v197, 0xffff0000, v234
	v_pk_mul_f32 v[136:137], v[136:137], v[196:197]
	v_cvt_pk_bf16_f32 v234, v136, v137
	v_pk_mul_f32 v[138:139], v[138:139], v[198:199] op_sel_hi:[1,0]
	v_lshlrev_b32_e32 v196, 16, v235
	v_and_b32_e32 v197, 0xffff0000, v235
	v_pk_mul_f32 v[138:139], v[138:139], v[196:197]
	v_cvt_pk_bf16_f32 v235, v138, v139
	v_pk_mul_f32 v[140:141], v[140:141], v[198:199] op_sel_hi:[1,0]
	v_lshlrev_b32_e32 v196, 16, v236
	v_and_b32_e32 v197, 0xffff0000, v236
	v_pk_mul_f32 v[140:141], v[140:141], v[196:197]
	v_cvt_pk_bf16_f32 v236, v140, v141
	v_pk_mul_f32 v[142:143], v[142:143], v[198:199] op_sel_hi:[1,0]
	v_lshlrev_b32_e32 v196, 16, v237
	v_and_b32_e32 v197, 0xffff0000, v237
	v_pk_mul_f32 v[142:143], v[142:143], v[196:197]
	v_cvt_pk_bf16_f32 v237, v142, v143
	v_pk_mul_f32 v[144:145], v[144:145], v[198:199] op_sel_hi:[1,0]
	v_lshlrev_b32_e32 v196, 16, v238
	v_and_b32_e32 v197, 0xffff0000, v238
	v_pk_mul_f32 v[144:145], v[144:145], v[196:197]
	v_cvt_pk_bf16_f32 v238, v144, v145
	v_pk_mul_f32 v[146:147], v[146:147], v[198:199] op_sel_hi:[1,0]
	v_lshlrev_b32_e32 v196, 16, v239
	v_and_b32_e32 v197, 0xffff0000, v239
	v_pk_mul_f32 v[146:147], v[146:147], v[196:197]
	v_cvt_pk_bf16_f32 v239, v146, v147
	v_pk_mul_f32 v[148:149], v[148:149], v[198:199] op_sel_hi:[1,0]
	v_lshlrev_b32_e32 v196, 16, v240
	v_and_b32_e32 v197, 0xffff0000, v240
	v_pk_mul_f32 v[148:149], v[148:149], v[196:197]
	v_cvt_pk_bf16_f32 v240, v148, v149
	v_pk_mul_f32 v[150:151], v[150:151], v[198:199] op_sel_hi:[1,0]
	v_lshlrev_b32_e32 v196, 16, v241
	v_and_b32_e32 v197, 0xffff0000, v241
	v_pk_mul_f32 v[150:151], v[150:151], v[196:197]
	v_cvt_pk_bf16_f32 v241, v150, v151
	v_pk_mul_f32 v[152:153], v[152:153], v[198:199] op_sel_hi:[1,0]
	v_lshlrev_b32_e32 v196, 16, v242
	v_and_b32_e32 v197, 0xffff0000, v242
	v_pk_mul_f32 v[152:153], v[152:153], v[196:197]
	v_cvt_pk_bf16_f32 v242, v152, v153
	v_pk_mul_f32 v[154:155], v[154:155], v[198:199] op_sel_hi:[1,0]
	v_lshlrev_b32_e32 v196, 16, v243
	v_and_b32_e32 v197, 0xffff0000, v243
	v_pk_mul_f32 v[154:155], v[154:155], v[196:197]
	v_cvt_pk_bf16_f32 v243, v154, v155
	v_pk_mul_f32 v[156:157], v[156:157], v[198:199] op_sel_hi:[1,0]
	v_lshlrev_b32_e32 v196, 16, v244
	v_and_b32_e32 v197, 0xffff0000, v244
	v_pk_mul_f32 v[156:157], v[156:157], v[196:197]
	v_cvt_pk_bf16_f32 v244, v156, v157
	v_pk_mul_f32 v[158:159], v[158:159], v[198:199] op_sel_hi:[1,0]
	v_lshlrev_b32_e32 v196, 16, v245
	v_and_b32_e32 v197, 0xffff0000, v245
	v_pk_mul_f32 v[158:159], v[158:159], v[196:197]
	v_cvt_pk_bf16_f32 v245, v158, v159
	v_pk_mul_f32 v[188:189], v[188:189], v[198:199] op_sel_hi:[1,0]
	v_lshlrev_b32_e32 v196, 16, v246
	v_and_b32_e32 v197, 0xffff0000, v246
	v_pk_mul_f32 v[188:189], v[188:189], v[196:197]
	v_cvt_pk_bf16_f32 v246, v188, v189
	v_pk_mul_f32 v[190:191], v[190:191], v[198:199] op_sel_hi:[1,0]
	v_lshlrev_b32_e32 v196, 16, v247
	v_and_b32_e32 v197, 0xffff0000, v247
	v_pk_mul_f32 v[190:191], v[190:191], v[196:197]
	v_cvt_pk_bf16_f32 v247, v190, v191
	s_branch .Lscan_ab_aftA
.Lscan_ab_noA:
	s_add_i32 s20, s97, 0x4280000
	v_add_u32_e32 v249, s20, v231
.Lscan_ab_aftA:
	s_add_i32 s20, s19, -1
	s_cmp_ge_u32 s20, s17
	s_cbranch_scc1 .Lscan_ab_nobody
	s_lshl_b32 s20, s20, 5
	s_add_i32 s20, s20, s96
	s_lshl_b32 s20, s20, 13
	s_add_i32 s20, s20, s97
	v_add_u32_e32 v250, s20, v231
	s_branch .Lscan_ab_noB
.Lscan_ab_nobody:
	s_add_i32 s20, s19, -2
	s_cmp_ge_u32 s20, s17
	s_cbranch_scc1 .Lscan_ab_noB
	v_readlane_b32 s100, v253, 53
	v_readlane_b32 s101, v253, 54
	s_nop 4
	global_store_dwordx4 v249, v[232:235], s[100:101]
	global_store_dwordx4 v249, v[236:239], s[100:101] offset:128
	global_store_dwordx4 v249, v[240:243], s[100:101] offset:256
	global_store_dwordx4 v249, v[244:247], s[100:101] offset:384
.Lscan_ab_noB:
	s_add_i32 s20, s19, -1
	s_cmp_ge_u32 s20, s17
	s_cbranch_scc1 .LBB0_320
	s_andn2_b32 s22, 1, s19
	s_mul_i32 s20, s22, 0x6c00
	s_lshl_b32 s21, s22, 14
	s_mul_i32 s22, s22, 0x8200
	v_add_u32_e32 v162, s20, v179
	v_add_u32_e32 v163, s20, v180
	v_add_u32_e32 v169, 0x2000, v162
	v_add_u32_e32 v171, 0x2000, v163
	v_readlane_b32 s100, v253, 53
	v_readlane_b32 s101, v253, 54
	ds_read2_b64 v[140:143], v169 offset0:32 offset1:36
	ds_read2_b64 v[132:135], v162 offset0:0 offset1:4
	ds_read2_b64 v[136:139], v163 offset0:0 offset1:4
	ds_read2_b64 v[144:147], v171 offset0:32 offset1:36
	ds_read2_b64 v[156:159], v169 offset0:40 offset1:44
	ds_read2_b64 v[148:151], v162 offset0:8 offset1:12
	ds_read2_b64 v[152:155], v163 offset0:8 offset1:12
	ds_read2_b64 v[188:191], v171 offset0:40 offset1:44
	v_add_u32_e32 v186, s21, v181
	v_add_u32_e32 v187, v186, v175
	v_add_u32_e32 v186, v186, v173
	ds_read_b64 v[216:217], v186 offset:55296
	ds_read_b64 v[218:219], v187 offset:55296
	ds_read_b64 v[220:221], v186 offset:56320
	ds_read_b64 v[222:223], v187 offset:56320
	v_cvt_pk_bf16_f32 v224, v4, v5
	v_cvt_pk_bf16_f32 v225, v6, v7
	v_cvt_pk_bf16_f32 v226, v20, v21
	v_cvt_pk_bf16_f32 v227, v22, v23
	v_mov_b32_e32 v3, v2
	s_waitcnt lgkmcnt(10)
	v_mfma_f32_16x16x32_bf16 v[192:195], v[140:143], v[132:135], 0
	s_waitcnt lgkmcnt(9)
	v_mfma_f32_16x16x32_bf16 v[196:199], v[140:143], v[136:139], 0
	s_waitcnt lgkmcnt(8)
	v_mfma_f32_16x16x32_bf16 v[200:203], v[144:147], v[136:139], 0
	ds_read2_b64 v[140:143], v169 offset0:48 offset1:52
	ds_read2_b64 v[132:135], v162 offset0:16 offset1:20
	ds_read2_b64 v[136:139], v163 offset0:16 offset1:20
	ds_read2_b64 v[144:147], v171 offset0:48 offset1:52
	global_store_dwordx4 v249, v[232:235], s[100:101]
	s_waitcnt lgkmcnt(10)
	v_mfma_f32_16x16x32_bf16 v[192:195], v[156:159], v[148:151], v[192:195]
	s_waitcnt lgkmcnt(9)
	v_mfma_f32_16x16x32_bf16 v[196:199], v[156:159], v[152:155], v[196:199]
	s_waitcnt lgkmcnt(8)
	v_mfma_f32_16x16x32_bf16 v[200:203], v[188:191], v[152:155], v[200:203]
	ds_read2_b64 v[156:159], v169 offset0:56 offset1:60
	ds_read2_b64 v[148:151], v162 offset0:24 offset1:28
	ds_read2_b64 v[152:155], v163 offset0:24 offset1:28
	ds_read2_b64 v[188:191], v171 offset0:56 offset1:60
	global_store_dwordx4 v249, v[236:239], s[100:101] offset:128
	s_waitcnt lgkmcnt(6)
	v_mfma_f32_16x16x32_bf16 v[192:195], v[140:143], v[132:135], v[192:195]
	s_waitcnt lgkmcnt(5)
	v_mfma_f32_16x16x32_bf16 v[196:199], v[140:143], v[136:139], v[196:199]
	s_waitcnt lgkmcnt(4)
	v_mfma_f32_16x16x32_bf16 v[200:203], v[144:147], v[136:139], v[200:203]
	global_store_dwordx4 v249, v[240:243], s[100:101] offset:256
	ds_read2_b64 v[132:135], v162 offset0:0 offset1:4
	ds_read2_b64 v[136:139], v163 offset0:0 offset1:4
	ds_read2_b64 v[140:143], v162 offset0:8 offset1:12
	ds_read2_b64 v[144:147], v163 offset0:8 offset1:12
	s_waitcnt lgkmcnt(6)
	v_mfma_f32_16x16x32_bf16 v[192:195], v[156:159], v[148:151], v[192:195]
	s_waitcnt lgkmcnt(5)
	v_mfma_f32_16x16x32_bf16 v[196:199], v[156:159], v[152:155], v[196:199]
	s_waitcnt lgkmcnt(4)
	v_mfma_f32_16x16x32_bf16 v[200:203], v[188:191], v[152:155], v[200:203]
	global_store_dwordx4 v249, v[244:247], s[100:101] offset:384
	v_readlane_b32 s100, v251, 22
	v_readlane_b32 s101, v251, 23
	v_add_u32_e32 v229, s22, v177
	v_add_u32_e32 v229, v229, v184
	v_add_u32_e32 v230, s20, v176
	v_add_u32_e32 v169, s20, v172
	v_add_u32_e32 v169, v169, v182
	v_add_u32_e32 v171, 0x4c00, v169
	v_add_u32_e32 v169, 0x4200, v169
	v_cndmask_b32_e64 v0, v192, 0, s[38:39]
	v_cndmask_b32_e64 v1, 0, v193, s[40:41]
	v_cndmask_b32_e64 v194, v194, 0, s[42:43]
	v_cndmask_b32_e64 v195, v195, 0, s[44:45]
	v_cvt_pk_bf16_f32 v0, v0, v1
	v_cvt_pk_bf16_f32 v1, v194, v195
	v_cndmask_b32_e64 v200, v200, 0, s[38:39]
	v_cndmask_b32_e64 v201, 0, v201, s[40:41]
	v_cndmask_b32_e64 v202, v202, 0, s[42:43]
	v_cndmask_b32_e64 v203, v203, 0, s[44:45]
	v_cvt_pk_bf16_f32 v192, v196, v197
	v_cvt_pk_bf16_f32 v193, v198, v199
	v_cvt_pk_bf16_f32 v194, v200, v201
	v_cvt_pk_bf16_f32 v195, v202, v203
	v_cvt_pk_bf16_f32 v196, v8, v9
	v_cvt_pk_bf16_f32 v197, v10, v11
	v_cvt_pk_bf16_f32 v198, v24, v25
	v_cvt_pk_bf16_f32 v199, v26, v27
	s_waitcnt lgkmcnt(3)
	v_mfma_f32_16x16x32_bf16 v[148:151], v[132:135], v[224:227], 0
	v_cvt_pk_bf16_f32 v200, v36, v37
	v_cvt_pk_bf16_f32 v201, v38, v39
	s_waitcnt lgkmcnt(2)
	v_mfma_f32_16x16x32_bf16 v[152:155], v[136:139], v[224:227], 0
	v_cvt_pk_bf16_f32 v202, v52, v53
	v_cvt_pk_bf16_f32 v203, v54, v55
	v_mfma_f32_16x16x32_bf16 v[156:159], v[132:135], v[196:199], 0
	v_cvt_pk_bf16_f32 v224, v40, v41
	v_cvt_pk_bf16_f32 v225, v42, v43
	v_mfma_f32_16x16x32_bf16 v[188:191], v[136:139], v[196:199], 0
	v_cvt_pk_bf16_f32 v226, v56, v57
	v_cvt_pk_bf16_f32 v227, v58, v59
	global_load_dwordx4 v[232:235], v250, s[100:101]
	ds_read2_b64 v[132:135], v162 offset0:16 offset1:20
	ds_read2_b64 v[136:139], v163 offset0:16 offset1:20
	s_waitcnt lgkmcnt(3)
	v_mfma_f32_16x16x32_bf16 v[148:151], v[140:143], v[200:203], v[148:151]
	v_cvt_pk_bf16_f32 v196, v68, v69
	v_cvt_pk_bf16_f32 v197, v70, v71
	s_waitcnt lgkmcnt(2)
	v_mfma_f32_16x16x32_bf16 v[152:155], v[144:147], v[200:203], v[152:155]
	v_cvt_pk_bf16_f32 v198, v84, v85
	v_cvt_pk_bf16_f32 v199, v86, v87
	v_mfma_f32_16x16x32_bf16 v[156:159], v[140:143], v[224:227], v[156:159]
	v_cvt_pk_bf16_f32 v200, v72, v73
	v_cvt_pk_bf16_f32 v201, v74, v75
	v_mfma_f32_16x16x32_bf16 v[188:191], v[144:147], v[224:227], v[188:191]
	v_cvt_pk_bf16_f32 v202, v88, v89
	v_cvt_pk_bf16_f32 v203, v90, v91
	global_load_dwordx4 v[236:239], v250, s[100:101] offset:128
	ds_read2_b64 v[140:143], v162 offset0:24 offset1:28
	ds_read2_b64 v[144:147], v163 offset0:24 offset1:28
	s_waitcnt lgkmcnt(3)
	v_mfma_f32_16x16x32_bf16 v[148:151], v[132:135], v[196:199], v[148:151]
	v_cvt_pk_bf16_f32 v224, v100, v101
	v_cvt_pk_bf16_f32 v225, v102, v103
	s_waitcnt lgkmcnt(2)
	v_mfma_f32_16x16x32_bf16 v[152:155], v[136:139], v[196:199], v[152:155]
	v_cvt_pk_bf16_f32 v226, v124, v125
	v_cvt_pk_bf16_f32 v227, v126, v127
	v_mfma_f32_16x16x32_bf16 v[156:159], v[132:135], v[200:203], v[156:159]
	v_cvt_pk_bf16_f32 v196, v104, v105
	v_cvt_pk_bf16_f32 v197, v106, v107
	v_mfma_f32_16x16x32_bf16 v[188:191], v[136:139], v[200:203], v[188:191]
	v_cvt_pk_bf16_f32 v198, v116, v117
	v_cvt_pk_bf16_f32 v199, v118, v119
	global_load_dwordx4 v[240:243], v250, s[100:101] offset:256
	s_waitcnt lgkmcnt(1)
	v_mfma_f32_16x16x32_bf16 v[148:151], v[140:143], v[224:227], v[148:151]
	v_cvt_pk_bf16_f32 v200, v12, v13
	v_cvt_pk_bf16_f32 v201, v14, v15
	s_waitcnt lgkmcnt(0)
	v_mfma_f32_16x16x32_bf16 v[152:155], v[144:147], v[224:227], v[152:155]
	v_cvt_pk_bf16_f32 v202, v28, v29
	v_cvt_pk_bf16_f32 v203, v30, v31
	v_mfma_f32_16x16x32_bf16 v[156:159], v[140:143], v[196:199], v[156:159]
	v_cvt_pk_bf16_f32 v224, v16, v17
	v_cvt_pk_bf16_f32 v225, v18, v19
	v_mfma_f32_16x16x32_bf16 v[188:191], v[144:147], v[196:199], v[188:191]
	v_cvt_pk_bf16_f32 v226, v32, v33
	v_cvt_pk_bf16_f32 v227, v34, v35
	global_load_dwordx4 v[244:247], v250, s[100:101] offset:384
	v_mfma_f32_16x16x32_bf16 v[148:151], v[0:3], v[216:219], v[148:151]
	v_mfma_f32_16x16x32_bf16 v[152:155], v[192:195], v[216:219], v[152:155]
	v_mfma_f32_16x16x32_bf16 v[156:159], v[0:3], v[220:223], v[156:159]
	v_mfma_f32_16x16x32_bf16 v[188:191], v[192:195], v[220:223], v[188:191]
	ds_read_b64 v[216:217], v186 offset:57344
	ds_read_b64 v[218:219], v187 offset:57344
	ds_read_b64 v[220:221], v186 offset:58368
	ds_read_b64 v[222:223], v187 offset:58368
	ds_read2_b64 v[132:135], v162 offset0:0 offset1:4
	ds_read2_b64 v[136:139], v163 offset0:0 offset1:4
	ds_read2_b64 v[140:143], v162 offset0:8 offset1:12
	ds_read2_b64 v[144:147], v163 offset0:8 offset1:12
	ds_write_b32 v229, v148 offset:0
	ds_write_b32 v229, v149 offset:1040
	ds_write_b32 v229, v150 offset:2080
	ds_write_b32 v229, v151 offset:3120
	s_waitcnt lgkmcnt(7)
	v_mfma_f32_16x16x32_bf16 v[148:151], v[132:135], v[200:203], 0
	v_cvt_pk_bf16_f32 v196, v44, v45
	v_cvt_pk_bf16_f32 v197, v46, v47
	ds_write_b32 v229, v152 offset:16640
	ds_write_b32 v229, v153 offset:17680
	ds_write_b32 v229, v154 offset:18720
	ds_write_b32 v229, v155 offset:19760
	s_waitcnt lgkmcnt(10)
	v_mfma_f32_16x16x32_bf16 v[152:155], v[136:139], v[200:203], 0
	v_cvt_pk_bf16_f32 v198, v60, v61
	v_cvt_pk_bf16_f32 v199, v62, v63
	ds_write_b32 v229, v156 offset:64
	ds_write_b32 v229, v157 offset:1104
	ds_write_b32 v229, v158 offset:2144
	ds_write_b32 v229, v159 offset:3184
	v_mfma_f32_16x16x32_bf16 v[156:159], v[132:135], v[224:227], 0
	v_cvt_pk_bf16_f32 v200, v48, v49
	v_cvt_pk_bf16_f32 v201, v50, v51
	ds_write_b32 v229, v188 offset:16704
	s_waitcnt lgkmcnt(14)
	ds_write_b32 v229, v189 offset:17744
	s_waitcnt lgkmcnt(14)
	ds_write_b32 v229, v190 offset:18784
	s_waitcnt lgkmcnt(14)
	ds_write_b32 v229, v191 offset:19824
	v_mfma_f32_16x16x32_bf16 v[188:191], v[136:139], v[224:227], 0
	v_cvt_pk_bf16_f32 v202, v64, v65
	v_cvt_pk_bf16_f32 v203, v66, v67
	s_waitcnt lgkmcnt(14)
	ds_read2_b64 v[132:135], v162 offset0:16 offset1:20
	s_waitcnt lgkmcnt(14)
	ds_read2_b64 v[136:139], v163 offset0:16 offset1:20
	v_mfma_f32_16x16x32_bf16 v[148:151], v[140:143], v[196:199], v[148:151]
	v_cvt_pk_bf16_f32 v224, v76, v77
	v_cvt_pk_bf16_f32 v225, v78, v79
	v_mfma_f32_16x16x32_bf16 v[152:155], v[144:147], v[196:199], v[152:155]
	v_cvt_pk_bf16_f32 v226, v92, v93
	v_cvt_pk_bf16_f32 v227, v94, v95
	v_mfma_f32_16x16x32_bf16 v[156:159], v[140:143], v[200:203], v[156:159]
	v_cvt_pk_bf16_f32 v196, v80, v81
	v_cvt_pk_bf16_f32 v197, v82, v83
	v_mfma_f32_16x16x32_bf16 v[188:191], v[144:147], v[200:203], v[188:191]
	v_cvt_pk_bf16_f32 v198, v96, v97
	v_cvt_pk_bf16_f32 v199, v98, v99
	s_waitcnt lgkmcnt(14)
	ds_read2_b64 v[140:143], v162 offset0:24 offset1:28
	s_waitcnt lgkmcnt(14)
	ds_read2_b64 v[144:147], v163 offset0:24 offset1:28
	s_waitcnt lgkmcnt(3)
	v_mfma_f32_16x16x32_bf16 v[148:151], v[132:135], v[224:227], v[148:151]
	v_cvt_pk_bf16_f32 v200, v108, v109
	v_cvt_pk_bf16_f32 v201, v110, v111
	s_waitcnt lgkmcnt(2)
	v_mfma_f32_16x16x32_bf16 v[152:155], v[136:139], v[224:227], v[152:155]
	v_cvt_pk_bf16_f32 v202, v120, v121
	v_cvt_pk_bf16_f32 v203, v122, v123
	v_mfma_f32_16x16x32_bf16 v[156:159], v[132:135], v[196:199], v[156:159]
	v_cvt_pk_bf16_f32 v224, v112, v113
	v_cvt_pk_bf16_f32 v225, v114, v115
	v_mfma_f32_16x16x32_bf16 v[188:191], v[136:139], v[196:199], v[188:191]
	v_cvt_pk_bf16_f32 v226, v128, v129
	v_cvt_pk_bf16_f32 v227, v130, v131
	ds_read_b64 v[132:133], v186 offset:55296
	ds_read_b64 v[134:135], v187 offset:55296
	ds_read_b64 v[136:137], v186 offset:56320
	ds_read_b64 v[138:139], v187 offset:56320
	s_waitcnt lgkmcnt(5)
	v_mfma_f32_16x16x32_bf16 v[148:151], v[140:143], v[200:203], v[148:151]
	s_waitcnt lgkmcnt(4)
	v_mfma_f32_16x16x32_bf16 v[152:155], v[144:147], v[200:203], v[152:155]
	v_mfma_f32_16x16x32_bf16 v[156:159], v[140:143], v[224:227], v[156:159]
	v_mfma_f32_16x16x32_bf16 v[188:191], v[144:147], v[224:227], v[188:191]
	v_add_u32_e32 v162, 0xa00, v171
	v_add_u32_e32 v163, 0x1400, v171
	ds_read2_b64 v[200:203], v169 offset0:0 offset1:4
	ds_read_b128 v[140:143], v230 offset:27136
	ds_read2_b64 v[224:227], v169 offset0:160 offset1:164
	ds_read_b128 v[144:147], v230 offset:27200
	v_mfma_f32_16x16x32_bf16 v[148:151], v[0:3], v[216:219], v[148:151]
	v_mfma_f32_16x16x32_bf16 v[152:155], v[192:195], v[216:219], v[152:155]
	v_mfma_f32_16x16x32_bf16 v[156:159], v[0:3], v[220:223], v[156:159]
	v_mfma_f32_16x16x32_bf16 v[188:191], v[192:195], v[220:223], v[188:191]
	ds_read2_b64 v[196:199], v171 offset0:0 offset1:4
	ds_read_b128 v[192:195], v230 offset:27264
	s_waitcnt lgkmcnt(5)
	v_mfma_f32_16x16x32_bf16 v[4:7], v[200:203], v[132:135], v[4:7]
	v_mfma_f32_16x16x32_bf16 v[8:11], v[200:203], v[136:139], v[8:11]
	v_mfma_f32_16x16x32_bf16 v[12:15], v[200:203], v[216:219], v[12:15]
	v_mfma_f32_16x16x32_bf16 v[16:19], v[200:203], v[220:223], v[16:19]
	ds_write_b32 v229, v148 offset:128
	ds_write_b32 v229, v149 offset:1168
	ds_write_b32 v229, v150 offset:2208
	ds_write_b32 v229, v151 offset:3248
	s_waitcnt lgkmcnt(7)
	v_mfma_f32_16x16x32_bf16 v[20:23], v[224:227], v[132:135], v[20:23]
	v_mfma_f32_16x16x32_bf16 v[24:27], v[224:227], v[136:139], v[24:27]
	v_mfma_f32_16x16x32_bf16 v[28:31], v[224:227], v[216:219], v[28:31]
	v_mfma_f32_16x16x32_bf16 v[32:35], v[224:227], v[220:223], v[32:35]
	v_pk_mul_f32 v[4:5], v[140:141], v[4:5]
	v_pk_mul_f32 v[6:7], v[142:143], v[6:7]
	v_pk_mul_f32 v[8:9], v[140:141], v[8:9]
	v_pk_mul_f32 v[10:11], v[142:143], v[10:11]
	v_pk_mul_f32 v[12:13], v[140:141], v[12:13]
	v_pk_mul_f32 v[14:15], v[142:143], v[14:15]
	v_pk_mul_f32 v[16:17], v[140:141], v[16:17]
	v_pk_mul_f32 v[18:19], v[142:143], v[18:19]
	ds_write_b32 v229, v152 offset:16768
	ds_write_b32 v229, v153 offset:17808
	ds_write_b32 v229, v154 offset:18848
	ds_write_b32 v229, v155 offset:19888
	ds_read2_b64 v[200:203], v171 offset0:160 offset1:164
	ds_read_b128 v[140:143], v230 offset:27328
	s_waitcnt lgkmcnt(11)
	v_mfma_f32_16x16x32_bf16 v[36:39], v[196:199], v[132:135], v[36:39]
	v_mfma_f32_16x16x32_bf16 v[40:43], v[196:199], v[136:139], v[40:43]
	v_mfma_f32_16x16x32_bf16 v[44:47], v[196:199], v[216:219], v[44:47]
	v_mfma_f32_16x16x32_bf16 v[48:51], v[196:199], v[220:223], v[48:51]
	v_pk_mul_f32 v[20:21], v[144:145], v[20:21]
	v_pk_mul_f32 v[22:23], v[146:147], v[22:23]
	v_pk_mul_f32 v[24:25], v[144:145], v[24:25]
	v_pk_mul_f32 v[26:27], v[146:147], v[26:27]
	v_pk_mul_f32 v[28:29], v[144:145], v[28:29]
	v_pk_mul_f32 v[30:31], v[146:147], v[30:31]
	v_pk_mul_f32 v[32:33], v[144:145], v[32:33]
	v_pk_mul_f32 v[34:35], v[146:147], v[34:35]
	ds_write_b32 v229, v156 offset:192
	ds_write_b32 v229, v157 offset:1232
	ds_write_b32 v229, v158 offset:2272
	ds_write_b32 v229, v159 offset:3312
	s_waitcnt lgkmcnt(14)
	ds_read2_b64 v[224:227], v162 offset0:0 offset1:4
	s_waitcnt lgkmcnt(14)
	ds_read_b128 v[144:147], v230 offset:27392
	s_waitcnt lgkmcnt(7)
	v_mfma_f32_16x16x32_bf16 v[52:55], v[200:203], v[132:135], v[52:55]
	v_mfma_f32_16x16x32_bf16 v[56:59], v[200:203], v[136:139], v[56:59]
	v_mfma_f32_16x16x32_bf16 v[60:63], v[200:203], v[216:219], v[60:63]
	v_mfma_f32_16x16x32_bf16 v[64:67], v[200:203], v[220:223], v[64:67]
	v_pk_mul_f32 v[36:37], v[192:193], v[36:37]
	v_pk_mul_f32 v[38:39], v[194:195], v[38:39]
	v_pk_mul_f32 v[40:41], v[192:193], v[40:41]
	v_pk_mul_f32 v[42:43], v[194:195], v[42:43]
	v_pk_mul_f32 v[44:45], v[192:193], v[44:45]
	v_pk_mul_f32 v[46:47], v[194:195], v[46:47]
	v_pk_mul_f32 v[48:49], v[192:193], v[48:49]
	v_pk_mul_f32 v[50:51], v[194:195], v[50:51]
	ds_write_b32 v229, v188 offset:16832
	ds_write_b32 v229, v189 offset:17872
	ds_write_b32 v229, v190 offset:18912
	ds_write_b32 v229, v191 offset:19952
	ds_read2_b64 v[196:199], v162 offset0:160 offset1:164
	ds_read_b128 v[192:195], v230 offset:27456
	s_waitcnt lgkmcnt(7)
	v_mfma_f32_16x16x32_bf16 v[68:71], v[224:227], v[132:135], v[68:71]
	v_mfma_f32_16x16x32_bf16 v[72:75], v[224:227], v[136:139], v[72:75]
	v_mfma_f32_16x16x32_bf16 v[76:79], v[224:227], v[216:219], v[76:79]
	v_mfma_f32_16x16x32_bf16 v[80:83], v[224:227], v[220:223], v[80:83]
	v_pk_mul_f32 v[52:53], v[140:141], v[52:53]
	v_pk_mul_f32 v[54:55], v[142:143], v[54:55]
	v_pk_mul_f32 v[56:57], v[140:141], v[56:57]
	v_pk_mul_f32 v[58:59], v[142:143], v[58:59]
	v_pk_mul_f32 v[60:61], v[140:141], v[60:61]
	v_pk_mul_f32 v[62:63], v[142:143], v[62:63]
	v_pk_mul_f32 v[64:65], v[140:141], v[64:65]
	v_pk_mul_f32 v[66:67], v[142:143], v[66:67]
	ds_read2_b64 v[200:203], v163 offset0:0 offset1:4
	ds_read_b128 v[140:143], v230 offset:27520
	s_waitcnt lgkmcnt(3)
	v_mfma_f32_16x16x32_bf16 v[84:87], v[196:199], v[132:135], v[84:87]
	v_mfma_f32_16x16x32_bf16 v[88:91], v[196:199], v[136:139], v[88:91]
	v_mfma_f32_16x16x32_bf16 v[92:95], v[196:199], v[216:219], v[92:95]
	v_mfma_f32_16x16x32_bf16 v[96:99], v[196:199], v[220:223], v[96:99]
	v_pk_mul_f32 v[68:69], v[144:145], v[68:69]
	v_pk_mul_f32 v[70:71], v[146:147], v[70:71]
	v_pk_mul_f32 v[72:73], v[144:145], v[72:73]
	v_pk_mul_f32 v[74:75], v[146:147], v[74:75]
	v_pk_mul_f32 v[76:77], v[144:145], v[76:77]
	v_pk_mul_f32 v[78:79], v[146:147], v[78:79]
	v_pk_mul_f32 v[80:81], v[144:145], v[80:81]
	v_pk_mul_f32 v[82:83], v[146:147], v[82:83]
	ds_read2_b64 v[224:227], v163 offset0:160 offset1:164
	ds_read_b128 v[144:147], v230 offset:27584
	s_waitcnt lgkmcnt(3)
	v_mfma_f32_16x16x32_bf16 v[100:103], v[200:203], v[132:135], v[100:103]
	v_mfma_f32_16x16x32_bf16 v[104:107], v[200:203], v[136:139], v[104:107]
	v_mfma_f32_16x16x32_bf16 v[108:111], v[200:203], v[216:219], v[108:111]
	v_mfma_f32_16x16x32_bf16 v[112:115], v[200:203], v[220:223], v[112:115]
	v_pk_mul_f32 v[84:85], v[192:193], v[84:85]
	v_pk_mul_f32 v[86:87], v[194:195], v[86:87]
	v_pk_mul_f32 v[88:89], v[192:193], v[88:89]
	v_pk_mul_f32 v[90:91], v[194:195], v[90:91]
	v_pk_mul_f32 v[92:93], v[192:193], v[92:93]
	v_pk_mul_f32 v[94:95], v[194:195], v[94:95]
	v_pk_mul_f32 v[96:97], v[192:193], v[96:97]
	v_pk_mul_f32 v[98:99], v[194:195], v[98:99]
	s_waitcnt lgkmcnt(1)
	v_mfma_f32_16x16x32_bf16 v[124:127], v[224:227], v[132:135], v[124:127]
	v_mfma_f32_16x16x32_bf16 v[116:119], v[224:227], v[136:139], v[116:119]
	v_mfma_f32_16x16x32_bf16 v[120:123], v[224:227], v[216:219], v[120:123]
	v_mfma_f32_16x16x32_bf16 v[128:131], v[224:227], v[220:223], v[128:131]
	v_pk_mul_f32 v[100:101], v[140:141], v[100:101]
	v_pk_mul_f32 v[102:103], v[142:143], v[102:103]
	v_pk_mul_f32 v[104:105], v[140:141], v[104:105]
	v_pk_mul_f32 v[106:107], v[142:143], v[106:107]
	v_pk_mul_f32 v[108:109], v[140:141], v[108:109]
	v_pk_mul_f32 v[110:111], v[142:143], v[110:111]
	v_pk_mul_f32 v[112:113], v[140:141], v[112:113]
	v_pk_mul_f32 v[114:115], v[142:143], v[114:115]
	s_waitcnt lgkmcnt(0)
	v_pk_mul_f32 v[124:125], v[144:145], v[124:125]
	v_pk_mul_f32 v[126:127], v[146:147], v[126:127]
	v_pk_mul_f32 v[116:117], v[144:145], v[116:117]
	v_pk_mul_f32 v[118:119], v[146:147], v[118:119]
	v_pk_mul_f32 v[120:121], v[144:145], v[120:121]
	v_pk_mul_f32 v[122:123], v[146:147], v[122:123]
	v_pk_mul_f32 v[128:129], v[144:145], v[128:129]
	v_pk_mul_f32 v[130:131], v[146:147], v[130:131]
	s_branch .LBB0_320
